# Resid HALFM tail K-loop rewritten: 3 LDS buffers (+16KB static LDS), one K-tile per 2 barriers, no wasted A-half staging
# speedup vs baseline: 1.0234x; 1.0234x over previous
.LBB0_786:
	v_mov_b32_e32 v39, v0
	v_lshl_add_u64 v[10:11], s[4:5], 0, v[38:39]
	v_mov_b32_e32 v35, v0
	v_lshl_add_u64 v[12:13], s[4:5], 0, v[34:35]
	v_mov_b32_e32 v41, v0
	s_add_i32 m0, s20, 0x18000
	v_lshl_add_u64 v[10:11], v[10:11], 0, s[76:77]
	v_lshl_add_u64 v[18:19], s[6:7], 0, v[40:41]
	v_mov_b32_e32 v37, v0
	s_waitcnt vmcnt(2)
	s_barrier
	global_load_lds_dwordx4 v[10:11], off
	v_lshl_add_u64 v[10:11], v[12:13], 0, s[76:77]
	s_add_i32 m0, s20, 0x1a000
	s_add_i32 s31, s20, 0x8000
	v_lshl_add_u64 v[20:21], s[6:7], 0, v[36:37]
	global_load_lds_dwordx4 v[10:11], off
	v_lshl_add_u64 v[10:11], v[18:19], 0, s[76:77]
	s_mov_b32 m0, s31
	s_add_i32 s34, s20, 0xa000
	v_lshl_add_u64 v[14:15], s[8:9], 0, v[38:39]
	global_load_lds_dwordx4 v[10:11], off
	v_lshl_add_u64 v[10:11], v[20:21], 0, s[76:77]
	s_mov_b32 m0, s34
	v_lshl_add_u64 v[16:17], s[8:9], 0, v[34:35]
	global_load_lds_dwordx4 v[10:11], off
	s_add_i32 m0, s20, 0x1c000
	v_lshl_add_u64 v[10:11], v[14:15], 0, s[76:77]
	global_load_lds_dwordx4 v[10:11], off
	v_lshl_add_u64 v[10:11], v[16:17], 0, s[76:77]
	s_add_i32 m0, s20, 0x1e000
	v_bfe_u32 v1, v5, 4, 2
	global_load_lds_dwordx4 v[10:11], off
	v_and_b32_e32 v9, 15, v5
	v_lshlrev_b32_e32 v22, 4, v1
	v_lshlrev_b32_e32 v5, 2, v5
	v_lshl_or_b32 v114, s15, 6, v9
	v_lshl_or_b32 v9, v9, 6, v22
	s_lshl_b32 s0, s15, 13
	v_and_b32_e32 v5, 32, v5
	v_bitop3_b32 v22, v9, s0, v5 bitop3:0xde
	s_lshl_b32 s0, s14, 5
	s_and_b32 s21, s0, 0x60
	s_lshl_b32 s0, s21, 7
	v_bitop3_b32 v54, v9, s0, v5 bitop3:0xde
	v_readlane_b32 s0, v254, 56
	s_add_i32 s35, s36, -2
	s_mul_i32 s0, s0, s1
	s_add_u32 s0, s10, s0
	s_addc_u32 s1, s11, 0
	s_add_u32 s0, s38, s0
	s_addc_u32 s1, s37, s1
	s_add_u32 s8, s0, 0x80
	v_add_u32_e32 v2, v4, v2
	s_waitcnt vmcnt(6)
	v_add_u32_e32 v5, v8, v6
	s_addc_u32 s9, s1, 0
	v_add_lshl_u32 v2, v2, v3, 1
	v_mov_b32_e32 v3, v0
	v_add_lshl_u32 v6, v5, v7, 1
	v_mov_b32_e32 v7, v0
	v_lshl_add_u64 v[52:53], s[8:9], 0, v[2:3]
	v_mov_b32_e32 v2, 0
	v_lshl_add_u64 v[50:51], s[8:9], 0, v[6:7]
	s_mov_b32 s14, 0
	s_mov_b64 s[8:9], 0
	v_add_u32_e32 v55, 0, v22
	v_mov_b32_e32 v3, v2
	v_mov_b32_e32 v4, v2
	v_mov_b32_e32 v5, v2
	v_mov_b32_e32 v6, v2
	v_mov_b32_e32 v7, v2
	v_mov_b32_e32 v8, v2
	v_mov_b32_e32 v9, v2
	v_mov_b32_e32 v18, v2
	v_mov_b32_e32 v19, v2
	v_mov_b32_e32 v20, v2
	v_mov_b32_e32 v21, v2
	v_mov_b32_e32 v22, v2
	v_mov_b32_e32 v23, v2
	v_mov_b32_e32 v24, v2
	v_mov_b32_e32 v25, v2
	v_mov_b32_e32 v42, v2
	v_mov_b32_e32 v43, v2
	v_mov_b32_e32 v44, v2
	v_mov_b32_e32 v45, v2
	v_mov_b32_e32 v46, v2
	v_mov_b32_e32 v47, v2
	v_mov_b32_e32 v48, v2
	v_mov_b32_e32 v49, v2
	v_mov_b32_e32 v82, v2
	v_mov_b32_e32 v83, v2
	v_mov_b32_e32 v84, v2
	v_mov_b32_e32 v85, v2
	v_mov_b32_e32 v86, v2
	v_mov_b32_e32 v87, v2
	v_mov_b32_e32 v88, v2
	v_mov_b32_e32 v89, v2
	v_mov_b32_e32 v10, v2
	v_mov_b32_e32 v11, v2
	v_mov_b32_e32 v12, v2
	v_mov_b32_e32 v13, v2
	v_mov_b32_e32 v14, v2
	v_mov_b32_e32 v15, v2
	v_mov_b32_e32 v16, v2
	v_mov_b32_e32 v17, v2
	v_mov_b32_e32 v26, v2
	v_mov_b32_e32 v27, v2
	v_mov_b32_e32 v28, v2
	v_mov_b32_e32 v29, v2
	v_mov_b32_e32 v30, v2
	v_mov_b32_e32 v31, v2
	v_mov_b32_e32 v32, v2
	v_mov_b32_e32 v33, v2
	v_mov_b32_e32 v70, v2
	v_mov_b32_e32 v71, v2
	v_mov_b32_e32 v72, v2
	v_mov_b32_e32 v73, v2
	v_mov_b32_e32 v78, v2
	v_mov_b32_e32 v79, v2
	v_mov_b32_e32 v80, v2
	v_mov_b32_e32 v81, v2
	v_mov_b32_e32 v90, v2
	v_mov_b32_e32 v91, v2
	v_mov_b32_e32 v92, v2
	v_mov_b32_e32 v93, v2
	v_mov_b32_e32 v94, v2
	v_mov_b32_e32 v95, v2
	v_mov_b32_e32 v96, v2
	v_mov_b32_e32 v97, v2
	s_barrier
	s_movk_i32 s8, 0x100
	s_lshl_b32 s9, s36, 7
	s_mov_b32 s14, 0
	v_add_u32_e32 v68, 0x10000, v54
	v_add_u32_e32 v69, 0x21c00, v54
.LBB0_787:
	s_add_u32 s40, s4, s8
	s_addc_u32 s41, s5, 0
	s_add_u32 s42, s40, s12
	s_addc_u32 s43, s41, 0
	s_add_u32 s10, s6, s8
	s_addc_u32 s11, s7, 0
	s_add_i32 m0, s20, 0xc000
	ds_read_b128 v[56:59], v68 offset:0
	global_load_lds_dwordx4 v38, s[40:41]
	s_add_i32 m0, s20, 0xe000
	ds_read_b128 v[60:63], v68 offset:1024
	global_load_lds_dwordx4 v34, s[40:41]
	s_add_i32 m0, s20, 0x21c00
	ds_read_b128 v[64:67], v68 offset:2048
	global_load_lds_dwordx4 v38, s[42:43]
	s_add_i32 m0, s20, 0x23c00
	ds_read_b128 v[74:77], v68 offset:3072
	global_load_lds_dwordx4 v34, s[42:43]
	s_add_i32 m0, s20, 0x4000
	ds_read_b128 v[116:119], v55 offset:0
	global_load_lds_dwordx4 v40, s[10:11]
	s_add_i32 m0, s20, 0x6000
	ds_read_b128 v[120:123], v55 offset:1024
	global_load_lds_dwordx4 v36, s[10:11]
	ds_read_b128 v[124:127], v55 offset:2048
	ds_read_b128 v[128:131], v55 offset:3072
	ds_read_b128 v[132:135], v55 offset:4096
	ds_read_b128 v[136:139], v55 offset:5120
	ds_read_b128 v[140:143], v55 offset:6144
	ds_read_b128 v[144:147], v55 offset:7168
	ds_read_b128 v[98:101], v68 offset:16384
	ds_read_b128 v[102:105], v68 offset:17408
	ds_read_b128 v[106:109], v68 offset:18432
	ds_read_b128 v[110:113], v68 offset:19456
	s_addk_i32 s8, 0x80
	s_cmp_eq_u32 s8, s9
	s_cselect_b32 s8, 0, s8
	s_waitcnt vmcnt(6)
	s_waitcnt lgkmcnt(0)
	s_barrier
	s_setprio 1
	v_mfma_f32_16x16x32_bf16 v[94:97], v[56:59], v[116:119], v[94:97]
	v_mfma_f32_16x16x32_bf16 v[90:93], v[64:67], v[116:119], v[90:93]
	v_mfma_f32_16x16x32_bf16 v[78:81], v[56:59], v[124:127], v[78:81]
	v_mfma_f32_16x16x32_bf16 v[70:73], v[64:67], v[124:127], v[70:73]
	v_mfma_f32_16x16x32_bf16 v[30:33], v[56:59], v[132:135], v[30:33]
	v_mfma_f32_16x16x32_bf16 v[26:29], v[64:67], v[132:135], v[26:29]
	v_mfma_f32_16x16x32_bf16 v[14:17], v[56:59], v[140:143], v[14:17]
	v_mfma_f32_16x16x32_bf16 v[10:13], v[64:67], v[140:143], v[10:13]
	v_mfma_f32_16x16x32_bf16 v[94:97], v[60:63], v[120:123], v[94:97]
	v_mfma_f32_16x16x32_bf16 v[90:93], v[74:77], v[120:123], v[90:93]
	v_mfma_f32_16x16x32_bf16 v[78:81], v[60:63], v[128:131], v[78:81]
	v_mfma_f32_16x16x32_bf16 v[70:73], v[74:77], v[128:131], v[70:73]
	v_mfma_f32_16x16x32_bf16 v[30:33], v[60:63], v[136:139], v[30:33]
	v_mfma_f32_16x16x32_bf16 v[26:29], v[74:77], v[136:139], v[26:29]
	v_mfma_f32_16x16x32_bf16 v[14:17], v[60:63], v[144:147], v[14:17]
	v_mfma_f32_16x16x32_bf16 v[10:13], v[74:77], v[144:147], v[10:13]
	v_mfma_f32_16x16x32_bf16 v[86:89], v[98:101], v[116:119], v[86:89]
	v_mfma_f32_16x16x32_bf16 v[82:85], v[106:109], v[116:119], v[82:85]
	v_mfma_f32_16x16x32_bf16 v[46:49], v[98:101], v[124:127], v[46:49]
	v_mfma_f32_16x16x32_bf16 v[42:45], v[106:109], v[124:127], v[42:45]
	v_mfma_f32_16x16x32_bf16 v[22:25], v[98:101], v[132:135], v[22:25]
	v_mfma_f32_16x16x32_bf16 v[18:21], v[106:109], v[132:135], v[18:21]
	v_mfma_f32_16x16x32_bf16 v[6:9], v[98:101], v[140:143], v[6:9]
	v_mfma_f32_16x16x32_bf16 v[2:5], v[106:109], v[140:143], v[2:5]
	v_mfma_f32_16x16x32_bf16 v[86:89], v[102:105], v[120:123], v[86:89]
	v_mfma_f32_16x16x32_bf16 v[82:85], v[110:113], v[120:123], v[82:85]
	v_mfma_f32_16x16x32_bf16 v[46:49], v[102:105], v[128:131], v[46:49]
	v_mfma_f32_16x16x32_bf16 v[42:45], v[110:113], v[128:131], v[42:45]
	v_mfma_f32_16x16x32_bf16 v[22:25], v[102:105], v[136:139], v[22:25]
	v_mfma_f32_16x16x32_bf16 v[18:21], v[110:113], v[136:139], v[18:21]
	v_mfma_f32_16x16x32_bf16 v[6:9], v[102:105], v[144:147], v[6:9]
	v_mfma_f32_16x16x32_bf16 v[2:5], v[110:113], v[144:147], v[2:5]
	s_setprio 0
	s_barrier
	s_add_i32 s14, s14, 1
	s_cmp_ge_u32 s14, s36
	s_cbranch_scc1 .Lrt_done
	s_add_u32 s40, s4, s8
	s_addc_u32 s41, s5, 0
	s_add_u32 s42, s40, s12
	s_addc_u32 s43, s41, 0
	s_add_u32 s10, s6, s8
	s_addc_u32 s11, s7, 0
	s_add_i32 m0, s20, 0x10000
	ds_read_b128 v[56:59], v68 offset:32768
	global_load_lds_dwordx4 v38, s[40:41]
	s_add_i32 m0, s20, 0x12000
	ds_read_b128 v[60:63], v68 offset:33792
	global_load_lds_dwordx4 v34, s[40:41]
	s_add_i32 m0, s20, 0x14000
	ds_read_b128 v[64:67], v68 offset:34816
	global_load_lds_dwordx4 v38, s[42:43]
	s_add_i32 m0, s20, 0x16000
	ds_read_b128 v[74:77], v68 offset:35840
	global_load_lds_dwordx4 v34, s[42:43]
	s_add_i32 m0, s20, 0x0
	ds_read_b128 v[116:119], v55 offset:32768
	global_load_lds_dwordx4 v40, s[10:11]
	s_add_i32 m0, s20, 0x2000
	ds_read_b128 v[120:123], v55 offset:33792
	global_load_lds_dwordx4 v36, s[10:11]
	ds_read_b128 v[124:127], v55 offset:34816
	ds_read_b128 v[128:131], v55 offset:35840
	ds_read_b128 v[132:135], v55 offset:36864
	ds_read_b128 v[136:139], v55 offset:37888
	ds_read_b128 v[140:143], v55 offset:38912
	ds_read_b128 v[144:147], v55 offset:39936
	ds_read_b128 v[98:101], v68 offset:49152
	ds_read_b128 v[102:105], v68 offset:50176
	ds_read_b128 v[106:109], v68 offset:51200
	ds_read_b128 v[110:113], v68 offset:52224
	s_addk_i32 s8, 0x80
	s_cmp_eq_u32 s8, s9
	s_cselect_b32 s8, 0, s8
	s_waitcnt vmcnt(6)
	s_waitcnt lgkmcnt(0)
	s_barrier
	s_setprio 1
	v_mfma_f32_16x16x32_bf16 v[94:97], v[56:59], v[116:119], v[94:97]
	v_mfma_f32_16x16x32_bf16 v[90:93], v[64:67], v[116:119], v[90:93]
	v_mfma_f32_16x16x32_bf16 v[78:81], v[56:59], v[124:127], v[78:81]
	v_mfma_f32_16x16x32_bf16 v[70:73], v[64:67], v[124:127], v[70:73]
	v_mfma_f32_16x16x32_bf16 v[30:33], v[56:59], v[132:135], v[30:33]
	v_mfma_f32_16x16x32_bf16 v[26:29], v[64:67], v[132:135], v[26:29]
	v_mfma_f32_16x16x32_bf16 v[14:17], v[56:59], v[140:143], v[14:17]
	v_mfma_f32_16x16x32_bf16 v[10:13], v[64:67], v[140:143], v[10:13]
	v_mfma_f32_16x16x32_bf16 v[94:97], v[60:63], v[120:123], v[94:97]
	v_mfma_f32_16x16x32_bf16 v[90:93], v[74:77], v[120:123], v[90:93]
	v_mfma_f32_16x16x32_bf16 v[78:81], v[60:63], v[128:131], v[78:81]
	v_mfma_f32_16x16x32_bf16 v[70:73], v[74:77], v[128:131], v[70:73]
	v_mfma_f32_16x16x32_bf16 v[30:33], v[60:63], v[136:139], v[30:33]
	v_mfma_f32_16x16x32_bf16 v[26:29], v[74:77], v[136:139], v[26:29]
	v_mfma_f32_16x16x32_bf16 v[14:17], v[60:63], v[144:147], v[14:17]
	v_mfma_f32_16x16x32_bf16 v[10:13], v[74:77], v[144:147], v[10:13]
	v_mfma_f32_16x16x32_bf16 v[86:89], v[98:101], v[116:119], v[86:89]
	v_mfma_f32_16x16x32_bf16 v[82:85], v[106:109], v[116:119], v[82:85]
	v_mfma_f32_16x16x32_bf16 v[46:49], v[98:101], v[124:127], v[46:49]
	v_mfma_f32_16x16x32_bf16 v[42:45], v[106:109], v[124:127], v[42:45]
	v_mfma_f32_16x16x32_bf16 v[22:25], v[98:101], v[132:135], v[22:25]
	v_mfma_f32_16x16x32_bf16 v[18:21], v[106:109], v[132:135], v[18:21]
	v_mfma_f32_16x16x32_bf16 v[6:9], v[98:101], v[140:143], v[6:9]
	v_mfma_f32_16x16x32_bf16 v[2:5], v[106:109], v[140:143], v[2:5]
	v_mfma_f32_16x16x32_bf16 v[86:89], v[102:105], v[120:123], v[86:89]
	v_mfma_f32_16x16x32_bf16 v[82:85], v[110:113], v[120:123], v[82:85]
	v_mfma_f32_16x16x32_bf16 v[46:49], v[102:105], v[128:131], v[46:49]
	v_mfma_f32_16x16x32_bf16 v[42:45], v[110:113], v[128:131], v[42:45]
	v_mfma_f32_16x16x32_bf16 v[22:25], v[102:105], v[136:139], v[22:25]
	v_mfma_f32_16x16x32_bf16 v[18:21], v[110:113], v[136:139], v[18:21]
	v_mfma_f32_16x16x32_bf16 v[6:9], v[102:105], v[144:147], v[6:9]
	v_mfma_f32_16x16x32_bf16 v[2:5], v[110:113], v[144:147], v[2:5]
	s_setprio 0
	s_barrier
	s_add_i32 s14, s14, 1
	s_cmp_ge_u32 s14, s36
	s_cbranch_scc1 .Lrt_done
	s_add_u32 s40, s4, s8
	s_addc_u32 s41, s5, 0
	s_add_u32 s42, s40, s12
	s_addc_u32 s43, s41, 0
	s_add_u32 s10, s6, s8
	s_addc_u32 s11, s7, 0
	s_add_i32 m0, s20, 0x18000
	ds_read_b128 v[56:59], v54 offset:49152
	global_load_lds_dwordx4 v38, s[40:41]
	s_add_i32 m0, s20, 0x1a000
	ds_read_b128 v[60:63], v54 offset:50176
	global_load_lds_dwordx4 v34, s[40:41]
	s_add_i32 m0, s20, 0x1c000
	ds_read_b128 v[64:67], v54 offset:51200
	global_load_lds_dwordx4 v38, s[42:43]
	s_add_i32 m0, s20, 0x1e000
	ds_read_b128 v[74:77], v54 offset:52224
	global_load_lds_dwordx4 v34, s[42:43]
	s_add_i32 m0, s20, 0x8000
	ds_read_b128 v[116:119], v55 offset:16384
	global_load_lds_dwordx4 v40, s[10:11]
	s_add_i32 m0, s20, 0xa000
	ds_read_b128 v[120:123], v55 offset:17408
	global_load_lds_dwordx4 v36, s[10:11]
	ds_read_b128 v[124:127], v55 offset:18432
	ds_read_b128 v[128:131], v55 offset:19456
	ds_read_b128 v[132:135], v55 offset:20480
	ds_read_b128 v[136:139], v55 offset:21504
	ds_read_b128 v[140:143], v55 offset:22528
	ds_read_b128 v[144:147], v55 offset:23552
	ds_read_b128 v[98:101], v69 offset:0
	ds_read_b128 v[102:105], v69 offset:1024
	ds_read_b128 v[106:109], v69 offset:2048
	ds_read_b128 v[110:113], v69 offset:3072
	s_addk_i32 s8, 0x80
	s_cmp_eq_u32 s8, s9
	s_cselect_b32 s8, 0, s8
	s_waitcnt vmcnt(6)
	s_waitcnt lgkmcnt(0)
	s_barrier
	s_setprio 1
	v_mfma_f32_16x16x32_bf16 v[94:97], v[56:59], v[116:119], v[94:97]
	v_mfma_f32_16x16x32_bf16 v[90:93], v[64:67], v[116:119], v[90:93]
	v_mfma_f32_16x16x32_bf16 v[78:81], v[56:59], v[124:127], v[78:81]
	v_mfma_f32_16x16x32_bf16 v[70:73], v[64:67], v[124:127], v[70:73]
	v_mfma_f32_16x16x32_bf16 v[30:33], v[56:59], v[132:135], v[30:33]
	v_mfma_f32_16x16x32_bf16 v[26:29], v[64:67], v[132:135], v[26:29]
	v_mfma_f32_16x16x32_bf16 v[14:17], v[56:59], v[140:143], v[14:17]
	v_mfma_f32_16x16x32_bf16 v[10:13], v[64:67], v[140:143], v[10:13]
	v_mfma_f32_16x16x32_bf16 v[94:97], v[60:63], v[120:123], v[94:97]
	v_mfma_f32_16x16x32_bf16 v[90:93], v[74:77], v[120:123], v[90:93]
	v_mfma_f32_16x16x32_bf16 v[78:81], v[60:63], v[128:131], v[78:81]
	v_mfma_f32_16x16x32_bf16 v[70:73], v[74:77], v[128:131], v[70:73]
	v_mfma_f32_16x16x32_bf16 v[30:33], v[60:63], v[136:139], v[30:33]
	v_mfma_f32_16x16x32_bf16 v[26:29], v[74:77], v[136:139], v[26:29]
	v_mfma_f32_16x16x32_bf16 v[14:17], v[60:63], v[144:147], v[14:17]
	v_mfma_f32_16x16x32_bf16 v[10:13], v[74:77], v[144:147], v[10:13]
	v_mfma_f32_16x16x32_bf16 v[86:89], v[98:101], v[116:119], v[86:89]
	v_mfma_f32_16x16x32_bf16 v[82:85], v[106:109], v[116:119], v[82:85]
	v_mfma_f32_16x16x32_bf16 v[46:49], v[98:101], v[124:127], v[46:49]
	v_mfma_f32_16x16x32_bf16 v[42:45], v[106:109], v[124:127], v[42:45]
	v_mfma_f32_16x16x32_bf16 v[22:25], v[98:101], v[132:135], v[22:25]
	v_mfma_f32_16x16x32_bf16 v[18:21], v[106:109], v[132:135], v[18:21]
	v_mfma_f32_16x16x32_bf16 v[6:9], v[98:101], v[140:143], v[6:9]
	v_mfma_f32_16x16x32_bf16 v[2:5], v[106:109], v[140:143], v[2:5]
	v_mfma_f32_16x16x32_bf16 v[86:89], v[102:105], v[120:123], v[86:89]
	v_mfma_f32_16x16x32_bf16 v[82:85], v[110:113], v[120:123], v[82:85]
	v_mfma_f32_16x16x32_bf16 v[46:49], v[102:105], v[128:131], v[46:49]
	v_mfma_f32_16x16x32_bf16 v[42:45], v[110:113], v[128:131], v[42:45]
	v_mfma_f32_16x16x32_bf16 v[22:25], v[102:105], v[136:139], v[22:25]
	v_mfma_f32_16x16x32_bf16 v[18:21], v[110:113], v[136:139], v[18:21]
	v_mfma_f32_16x16x32_bf16 v[6:9], v[102:105], v[144:147], v[6:9]
	v_mfma_f32_16x16x32_bf16 v[2:5], v[110:113], v[144:147], v[2:5]
	s_setprio 0
	s_barrier
	s_add_i32 s14, s14, 1
	s_cmp_lt_u32 s14, s36
	s_cbranch_scc1 .LBB0_787
.Lrt_done:
	s_cmpk_lt_u32 s3, 0x100
	s_cbranch_scc0 .LBB0_790
	s_barrier

	.amdhsa_kernel _Z10fwd_kernel6Params
		.amdhsa_group_segment_fixed_size 16384
		.amdhsa_private_segment_fixed_size 0
		.amdhsa_kernarg_size 464
		.amdhsa_user_sgpr_count 2
		.amdhsa_user_sgpr_dispatch_ptr 0
		.amdhsa_user_sgpr_queue_ptr 0
		.amdhsa_user_sgpr_kernarg_segment_ptr 1
		.amdhsa_user_sgpr_dispatch_id 0
		.amdhsa_user_sgpr_kernarg_preload_length 0
		.amdhsa_user_sgpr_kernarg_preload_offset 0
		.amdhsa_user_sgpr_private_segment_size 0
		.amdhsa_uses_dynamic_stack 0
		.amdhsa_enable_private_segment 0
		.amdhsa_system_sgpr_workgroup_id_x 1
		.amdhsa_system_sgpr_workgroup_id_y 0
		.amdhsa_system_sgpr_workgroup_id_z 0
		.amdhsa_system_sgpr_workgroup_info 0
		.amdhsa_system_vgpr_workitem_id 2
		.amdhsa_next_free_vgpr 256
		.amdhsa_next_free_sgpr 102
		.amdhsa_accum_offset 256
		.amdhsa_reserve_vcc 1
		.amdhsa_float_round_mode_32 0
		.amdhsa_float_round_mode_16_64 0
		.amdhsa_float_denorm_mode_32 3
		.amdhsa_float_denorm_mode_16_64 3
		.amdhsa_dx10_clamp 1
		.amdhsa_ieee_mode 1
		.amdhsa_fp16_overflow 0
		.amdhsa_tg_split 0
		.amdhsa_exception_fp_ieee_invalid_op 0
		.amdhsa_exception_fp_denorm_src 0
		.amdhsa_exception_fp_ieee_div_zero 0
		.amdhsa_exception_fp_ieee_overflow 0
		.amdhsa_exception_fp_ieee_underflow 0
		.amdhsa_exception_fp_ieee_inexact 0
		.amdhsa_exception_int_div_zero 0
	.end_amdhsa_kernel

amdhsa.kernels:
  - .agpr_count:     0
    .args:
      - .offset:         0
        .size:           208
        .value_kind:     by_value
      - .offset:         208
        .size:           4
        .value_kind:     hidden_block_count_x
      - .offset:         212
        .size:           4
        .value_kind:     hidden_block_count_y
      - .offset:         216
        .size:           4
        .value_kind:     hidden_block_count_z
      - .offset:         220
        .size:           2
        .value_kind:     hidden_group_size_x
      - .offset:         222
        .size:           2
        .value_kind:     hidden_group_size_y
      - .offset:         224
        .size:           2
        .value_kind:     hidden_group_size_z
      - .offset:         226
        .size:           2
        .value_kind:     hidden_remainder_x
      - .offset:         228
        .size:           2
        .value_kind:     hidden_remainder_y
      - .offset:         230
        .size:           2
        .value_kind:     hidden_remainder_z
      - .offset:         248
        .size:           8
        .value_kind:     hidden_global_offset_x
      - .offset:         256
        .size:           8
        .value_kind:     hidden_global_offset_y
      - .offset:         264
        .size:           8
        .value_kind:     hidden_global_offset_z
      - .offset:         272
        .size:           2
        .value_kind:     hidden_grid_dims
      - .offset:         296
        .size:           8
        .value_kind:     hidden_multigrid_sync_arg
      - .offset:         328
        .size:           4
        .value_kind:     hidden_dynamic_lds_size
    .group_segment_fixed_size: 16384
    .kernarg_segment_align: 8
    .kernarg_segment_size: 464
    .language:       OpenCL C
    .language_version:
      - 2
      - 0
    .max_flat_workgroup_size: 512
    .name:           _Z10fwd_kernel6Params
    .private_segment_fixed_size: 0
    .sgpr_count:     108
    .sgpr_spill_count: 99
    .symbol:         _Z10fwd_kernel6Params.kd
    .uniform_work_group_size: 1
    .uses_dynamic_stack: false
    .vgpr_count:     256
    .vgpr_spill_count: 0
    .wavefront_size: 64
